# attention loop vote: combined max and compare issued ahead of the last P.V MFMA (temp renamed, s_nop dropped), one SALU trimmed from the uniform-branch test (docs 7.12)
# baseline (speedup 1.0000x reference)
.LBB0_963:
	s_add_u32 s36, s28, s30
	s_addc_u32 s37, s29, s31
	s_add_u32 s34, s36, 0x100000
	s_addc_u32 s35, s37, 0
	s_lshl_b32 s9, s19, 14
	s_add_i32 s48, s95, s9
	s_mov_b32 m0, s48
	s_nop 0
	global_load_lds_dwordx4 v228, s[34:35]
	s_add_i32 m0, s48, 0x400
	s_nop 0
	global_load_lds_dwordx4 v231, s[34:35]
	ds_read_b128 v[236:239], v196 offset:12288
	s_waitcnt lgkmcnt(3)
	v_mfma_f32_16x16x32_bf16 v[120:123], v[184:187], v[36:39], v[120:123]
	v_exp_f32_e32 v196, v132
	v_exp_f32_e32 v208, v133
	v_add_f32_e32 v206, v152, v206
	v_add_f32_e32 v207, v136, v207
	v_mfma_f32_16x16x32_bf16 v[124:127], v[184:187], v[0:3], v[124:127]
	v_add_u32_e32 v209, s25, v233
	ds_read_b128 v[184:187], v209
	v_exp_f32_e32 v210, v134
	v_exp_f32_e32 v211, v135
	s_waitcnt lgkmcnt(3)
	v_mfma_f32_16x16x32_bf16 v[132:135], v[176:179], v[0:3], v[148:151]
	v_mfma_f32_16x16x32_bf16 v[160:163], v[176:179], v[36:39], v[160:163]
	s_nop 1
	v_add_f32_e32 v148, v153, v206
	v_add_f32_e32 v149, v137, v207
	ds_read_b128 v[176:179], v209 offset:4096
	s_waitcnt lgkmcnt(3)
	v_mfma_f32_16x16x32_bf16 v[164:167], v[180:183], v[0:3], v[164:167]
	v_exp_f32_e32 v212, v128
	v_exp_f32_e32 v213, v129
	v_add_f32_e32 v148, v154, v148
	v_mfma_f32_16x16x32_bf16 v[168:171], v[180:183], v[36:39], v[168:171]
	v_add_f32_e32 v149, v138, v149
	ds_read_b128 v[180:183], v209 offset:8192
	v_exp_f32_e32 v219, v130
	v_exp_f32_e32 v235, v131
	s_waitcnt lgkmcnt(3)
	v_mfma_f32_16x16x32_bf16 v[128:131], v[236:239], v[0:3], v[140:143]
	v_add_f32_e32 v148, v155, v148
	v_add_f32_e32 v149, v139, v149
	v_mfma_f32_16x16x32_bf16 v[140:143], v[236:239], v[36:39], v[172:175]
	s_nop 2
	ds_read_b128 v[172:175], v209 offset:12288
	s_waitcnt lgkmcnt(3)
	v_mfma_f32_16x16x32_bf16 v[120:123], v[184:187], v[28:31], v[120:123]
	v_add_f32_e32 v150, v188, v148
	v_add_f32_e32 v149, v190, v149
	v_mfma_f32_16x16x32_bf16 v[124:127], v[184:187], v[12:15], v[124:127]
	v_cvt_pk_bf16_f32 v148, v156, v157
	v_add_u32_e32 v206, s25, v230
	ds_read_b128 v[184:187], v206
	v_add_f32_e32 v150, v189, v150
	v_add_f32_e32 v151, v191, v149
	s_waitcnt lgkmcnt(3)
	v_mfma_f32_16x16x32_bf16 v[132:135], v[176:179], v[12:15], v[132:135]
	v_cvt_pk_bf16_f32 v149, v158, v159
	v_mfma_f32_16x16x32_bf16 v[156:159], v[176:179], v[28:31], v[160:163]
	ds_read_b128 v[176:179], v206 offset:4096
	s_waitcnt lgkmcnt(3)
	v_mfma_f32_16x16x32_bf16 v[162:165], v[180:183], v[12:15], v[164:167]
	s_nop 0
	v_add_f32_e32 v160, v194, v150
	v_add_f32_e32 v151, v192, v151
	v_mfma_f32_16x16x32_bf16 v[166:169], v[180:183], v[28:31], v[168:171]
	v_cvt_pk_bf16_f32 v150, v152, v153
	ds_read_b128 v[180:183], v206 offset:8192
	s_waitcnt lgkmcnt(3)
	v_mfma_f32_16x16x32_bf16 v[128:131], v[172:175], v[12:15], v[128:131]
	v_add_f32_e32 v160, v195, v160
	v_add_f32_e32 v161, v193, v151
	v_mfma_f32_16x16x32_bf16 v[140:143], v[172:175], v[28:31], v[140:143]
	v_cvt_pk_bf16_f32 v151, v154, v155
	ds_read_b128 v[152:155], v206 offset:12288
	s_waitcnt lgkmcnt(3)
	v_mfma_f32_16x16x32_bf16 v[120:123], v[184:187], v[24:27], v[120:123]
	v_add_f32_e32 v174, v196, v160
	v_add_f32_e32 v161, v212, v161
	v_mfma_f32_16x16x32_bf16 v[124:127], v[184:187], v[8:11], v[124:127]
	v_cvt_pk_bf16_f32 v160, v144, v145
	v_add_u32_e32 v186, s25, v226
	ds_read_b128 v[170:173], v186 offset:16384
	v_add_f32_e32 v184, v208, v174
	v_add_f32_e32 v185, v213, v161
	s_waitcnt lgkmcnt(3)
	v_mfma_f32_16x16x32_bf16 v[132:135], v[176:179], v[8:11], v[132:135]
	v_cvt_pk_bf16_f32 v161, v146, v147
	v_mfma_f32_16x16x32_bf16 v[144:147], v[176:179], v[24:27], v[156:159]
	s_nop 2
	ds_read_b128 v[156:159], v186 offset:18432
	s_waitcnt lgkmcnt(3)
	v_mfma_f32_16x16x32_bf16 v[174:177], v[180:183], v[8:11], v[162:165]
	v_mfma_f32_16x16x32_bf16 v[178:181], v[180:183], v[24:27], v[166:169]
	s_nop 1
	v_add_f32_e32 v163, v210, v184
	v_add_f32_e32 v164, v219, v185
	v_cvt_pk_bf16_f32 v162, v136, v137
	ds_read_b128 v[182:185], v186 offset:20480
	v_add_f32_e32 v206, v211, v163
	v_add_f32_e32 v207, v235, v164
	s_waitcnt lgkmcnt(3)
	v_mfma_f32_16x16x32_bf16 v[128:131], v[152:155], v[8:11], v[128:131]
	v_cvt_pk_bf16_f32 v163, v138, v139
	v_mfma_f32_16x16x32_bf16 v[136:139], v[152:155], v[24:27], v[140:143]
	s_nop 2
	ds_read_b128 v[140:143], v186 offset:22528
	s_waitcnt lgkmcnt(3)
	v_mfma_f32_16x16x32_bf16 v[120:123], v[170:173], v[32:35], v[120:123]
	v_cvt_pk_bf16_f32 v164, v188, v189
	v_mfma_f32_16x16x32_bf16 v[124:127], v[170:173], v[16:19], v[124:127]
	v_add_u32_e32 v152, s25, v224
	ds_read_b128 v[168:171], v152 offset:16384
	s_waitcnt lgkmcnt(3)
	v_mfma_f32_16x16x32_bf16 v[132:135], v[156:159], v[16:19], v[132:135]
	v_cvt_pk_bf16_f32 v165, v194, v195
	v_mfma_f32_16x16x32_bf16 v[186:189], v[156:159], v[32:35], v[144:147]
	ds_read_b128 v[236:239], v152 offset:18432
	s_waitcnt lgkmcnt(3)
	v_mfma_f32_16x16x32_bf16 v[240:243], v[182:185], v[16:19], v[174:177]
	v_cvt_pk_bf16_f32 v166, v196, v208
	v_mfma_f32_16x16x32_bf16 v[176:179], v[182:185], v[32:35], v[178:181]
	s_nop 2
	ds_read_b128 v[180:183], v152 offset:20480
	s_waitcnt lgkmcnt(3)
	v_mfma_f32_16x16x32_bf16 v[128:131], v[140:143], v[16:19], v[128:131]
	v_cvt_pk_bf16_f32 v167, v210, v211
	v_mfma_f32_16x16x32_bf16 v[244:247], v[140:143], v[32:35], v[136:139]
	ds_read_b128 v[248:251], v152 offset:22528
	s_waitcnt lgkmcnt(3)
	v_mfma_f32_16x16x32_bf16 v[152:155], v[168:171], v[20:23], v[124:127]
	v_mfma_f32_16x16x32_bf16 v[144:147], v[168:171], v[44:47], v[120:123]
	v_cvt_pk_bf16_f32 v168, v190, v191
	s_waitcnt lgkmcnt(2)
	v_mfma_f32_16x16x32_bf16 v[156:159], v[236:239], v[20:23], v[132:135]
	v_cvt_pk_bf16_f32 v169, v192, v193
	v_mfma_f32_16x16x32_bf16 v[172:175], v[236:239], v[44:47], v[186:189]
	s_waitcnt lgkmcnt(1)
	v_mfma_f32_16x16x32_bf16 v[140:143], v[180:183], v[20:23], v[240:243]
	v_cvt_pk_bf16_f32 v170, v212, v213
	v_mfma_f32_16x16x32_bf16 v[136:139], v[180:183], v[44:47], v[176:179]
	s_waitcnt lgkmcnt(0)
	v_mfma_f32_16x16x32_bf16 v[132:135], v[248:251], v[20:23], v[128:131]
	v_cvt_pk_bf16_f32 v171, v219, v235
	v_mfma_f32_16x16x32_bf16 v[128:131], v[248:251], v[44:47], v[244:247]
	s_lshl_b32 s34, s8, 14
	s_add_i32 s48, s34, 0
	s_add_i32 s48, s48, 0x12000
	v_add_u32_e32 v196, s48, v222
	v_add_u32_e32 v219, s48, v223
	ds_read_b64_tr_b16 v[176:177], v219
	ds_read_b64_tr_b16 v[178:179], v219 offset:4096
	ds_read_b64_tr_b16 v[184:185], v219 offset:8192
	ds_read_b64_tr_b16 v[186:187], v219 offset:12288
	ds_read_b64_tr_b16 v[120:121], v196
	ds_read_b64_tr_b16 v[122:123], v196 offset:4096
	ds_read_b64_tr_b16 v[124:125], v196 offset:8192
	ds_read_b64_tr_b16 v[126:127], v196 offset:12288
	ds_read_b64_tr_b16 v[182:183], v219 offset:4608
	ds_read_b64_tr_b16 v[180:181], v219 offset:512
	ds_read_b64_tr_b16 v[190:191], v219 offset:12800
	ds_read_b64_tr_b16 v[188:189], v219 offset:8704
	s_waitcnt lgkmcnt(10)
	v_mfma_f32_16x16x32_bf16 v[112:115], v[176:179], v[148:151], v[112:115]
	v_mfma_f32_16x16x32_bf16 v[116:119], v[176:179], v[160:163], v[116:119]
	v_max_f32_e32 v176, v152, v153
	s_waitcnt lgkmcnt(8)
	v_mfma_f32_16x16x32_bf16 v[112:115], v[184:187], v[164:167], v[112:115]
	v_max3_f32 v176, v176, v154, v155
	v_max3_f32 v176, v176, v156, v157
	v_max3_f32 v208, v176, v158, v159
	v_mfma_f32_16x16x32_bf16 v[116:119], v[184:187], v[168:171], v[116:119]
	ds_read_b64_tr_b16 v[192:193], v196 offset:512
	ds_read_b64_tr_b16 v[194:195], v196 offset:4608
	ds_read_b64_tr_b16 v[236:237], v196 offset:8704
	ds_read_b64_tr_b16 v[238:239], v196 offset:12800
	s_waitcnt lgkmcnt(10)
	v_mfma_f32_16x16x32_bf16 v[108:111], v[120:123], v[148:151], v[108:111]
	v_mfma_f32_16x16x32_bf16 v[176:179], v[120:123], v[160:163], v[104:107]
	s_waitcnt lgkmcnt(8)
	v_mfma_f32_16x16x32_bf16 v[104:107], v[124:127], v[164:167], v[108:111]
	s_nop 5
	v_max3_f32 v108, v208, v140, v141
	v_max3_f32 v108, v108, v142, v143
	v_max3_f32 v108, v108, v132, v133
	v_max3_f32 v120, v108, v134, v135
	v_mfma_f32_16x16x32_bf16 v[108:111], v[124:127], v[168:171], v[176:179]
	ds_read_b64_tr_b16 v[184:185], v219 offset:1024
	ds_read_b64_tr_b16 v[186:187], v219 offset:5120
	s_nop 0
	ds_read_b64_tr_b16 v[176:177], v219 offset:9216
	ds_read_b64_tr_b16 v[178:179], v219 offset:13312
	s_waitcnt lgkmcnt(10)
	v_mfma_f32_16x16x32_bf16 v[96:99], v[180:183], v[148:151], v[96:99]
	v_max_f32_e32 v121, v144, v145
	s_waitcnt lgkmcnt(8)
	v_mfma_f32_16x16x32_bf16 v[96:99], v[188:191], v[164:167], v[96:99]
	v_max3_f32 v121, v121, v146, v147
	v_max3_f32 v121, v121, v172, v173
	v_max3_f32 v121, v121, v174, v175
	v_mfma_f32_16x16x32_bf16 v[100:103], v[180:183], v[160:163], v[100:103]
	v_mfma_f32_16x16x32_bf16 v[100:103], v[188:191], v[168:171], v[100:103]
	ds_read_b64_tr_b16 v[188:189], v196 offset:1024
	ds_read_b64_tr_b16 v[190:191], v196 offset:5120
	ds_read_b64_tr_b16 v[180:181], v196 offset:9216
	ds_read_b64_tr_b16 v[182:183], v196 offset:13312
	s_waitcnt lgkmcnt(10)
	v_mfma_f32_16x16x32_bf16 v[92:95], v[192:195], v[148:151], v[92:95]
	v_mfma_f32_16x16x32_bf16 v[122:125], v[192:195], v[160:163], v[88:91]
	s_waitcnt lgkmcnt(8)
	v_mfma_f32_16x16x32_bf16 v[88:91], v[236:239], v[164:167], v[92:95]
	s_nop 5
	v_max3_f32 v92, v121, v136, v137
	v_max3_f32 v92, v92, v138, v139
	v_max3_f32 v92, v92, v128, v129
	v_max3_f32 v121, v92, v130, v131
	v_max_f32_e32 v252, v120, v121
	v_cmp_ge_f32_e32 vcc, s62, v252
	v_mfma_f32_16x16x32_bf16 v[92:95], v[236:239], v[168:171], v[122:125]
	s_cmp_eq_u64 vcc, exec
	s_cselect_b64 s[34:35], 0, -1
	s_cbranch_scc1 .LBB0_965
	ds_bpermute_b32 v48, v220, v120
	v_max_f32_e32 v49, v120, v120
	v_max_f32_e32 v50, v121, v121
	s_waitcnt lgkmcnt(0)
	v_max_f32_e32 v48, v48, v48
	v_max_f32_e32 v48, v49, v48
	ds_bpermute_b32 v49, v221, v48
	s_waitcnt lgkmcnt(0)
	v_max3_f32 v48, v48, v49, 0
	ds_bpermute_b32 v49, v220, v121
	v_exp_f32_e64 v208, -v48
	v_sub_f32_e32 v152, v152, v48
	v_sub_f32_e32 v153, v153, v48
	v_sub_f32_e32 v154, v154, v48
	s_waitcnt lgkmcnt(0)
	v_max_f32_e32 v49, v49, v49
	v_max_f32_e32 v49, v50, v49
	ds_bpermute_b32 v50, v221, v49
	v_sub_f32_e32 v155, v155, v48
	v_sub_f32_e32 v156, v156, v48
	v_sub_f32_e32 v157, v157, v48
	v_sub_f32_e32 v158, v158, v48
	s_waitcnt lgkmcnt(0)
	v_max3_f32 v49, v49, v50, 0
	v_exp_f32_e64 v209, -v49
	v_pk_add_f32 v[202:203], v[202:203], v[48:49]
	v_sub_f32_e32 v159, v159, v48
	v_pk_add_f32 v[120:121], v[202:203], 0 neg_lo:[1,1] neg_hi:[1,1]
	v_xor_b32_e32 v124, 0x80000000, v203
	v_sub_f32_e32 v143, v143, v48
	v_sub_f32_e32 v142, v142, v48
	v_sub_f32_e32 v141, v141, v48
	v_sub_f32_e32 v140, v140, v48
	v_sub_f32_e32 v135, v135, v48
	v_sub_f32_e32 v134, v134, v48
	v_sub_f32_e32 v133, v133, v48
	v_sub_f32_e32 v132, v132, v48
	v_mov_b32_e32 v121, v120
	v_mov_b32_e32 v122, v120
	v_mov_b32_e32 v123, v120
	v_sub_f32_e32 v144, v144, v49
	v_sub_f32_e32 v145, v145, v49
	v_sub_f32_e32 v146, v146, v49
	v_sub_f32_e32 v147, v147, v49
	v_sub_f32_e32 v172, v172, v49
	v_sub_f32_e32 v173, v173, v49
	v_sub_f32_e32 v174, v174, v49
	v_sub_f32_e32 v175, v175, v49
	v_sub_f32_e32 v139, v139, v49
	v_sub_f32_e32 v138, v138, v49
	v_sub_f32_e32 v137, v137, v49
	v_sub_f32_e32 v136, v136, v49
	v_sub_f32_e32 v131, v131, v49
	v_sub_f32_e32 v130, v130, v49
	v_sub_f32_e32 v129, v129, v49
	v_sub_f32_e32 v128, v128, v49
	v_mov_b32_e32 v125, v124
	v_mov_b32_e32 v126, v124
	v_mov_b32_e32 v127, v124
	v_mov_b32_e32 v48, v120
	v_mov_b32_e32 v49, v120
	v_mov_b32_e32 v50, v120
	v_mov_b32_e32 v51, v120
	v_mov_b32_e32 v52, v124
	v_mov_b32_e32 v53, v124
	v_mov_b32_e32 v54, v124
	v_mov_b32_e32 v55, v124
	s_branch .LBB0_966

.LBB0_971:
	s_add_u32 s36, s36, 0x180000
	s_addc_u32 s37, s37, 0
	s_add_i32 s25, s48, s77
	s_mov_b32 m0, s25
	s_nop 0
	global_load_lds_dwordx4 v228, s[36:37]
	s_add_i32 m0, s25, 0x400
	s_nop 0
	global_load_lds_dwordx4 v231, s[36:37]
	ds_read_b128 v[246:249], v243 offset:12288
	s_waitcnt lgkmcnt(3)
	v_mfma_f32_16x16x32_bf16 v[164:167], v[192:195], v[0:3], v[164:167]
	v_exp_f32_e32 v210, v132
	v_exp_f32_e32 v211, v133
	v_add_f32_e32 v212, v156, v245
	v_mfma_f32_16x16x32_bf16 v[160:163], v[192:195], v[36:39], v[160:163]
	v_add_f32_e32 v213, v148, v244
	v_add_u32_e32 v243, s49, v233
	ds_read_b128 v[192:195], v243
	v_exp_f32_e32 v250, v134
	v_exp_f32_e32 v251, v135
	s_waitcnt lgkmcnt(3)
	v_mfma_f32_16x16x32_bf16 v[132:135], v[188:191], v[0:3], v[180:183]
	v_add_f32_e32 v212, v157, v212
	v_add_f32_e32 v213, v149, v213
	v_mfma_f32_16x16x32_bf16 v[172:175], v[188:191], v[36:39], v[172:175]
	ds_read_b128 v[180:183], v243 offset:4096
	s_waitcnt lgkmcnt(3)
	v_mfma_f32_16x16x32_bf16 v[176:179], v[184:187], v[0:3], v[176:179]
	v_exp_f32_e32 v215, v128
	v_exp_f32_e32 v214, v129
	v_add_f32_e32 v188, v158, v212
	v_mfma_f32_16x16x32_bf16 v[140:143], v[184:187], v[36:39], v[140:143]
	v_add_f32_e32 v189, v150, v213
	ds_read_b128 v[184:187], v243 offset:8192
	v_exp_f32_e32 v218, v130
	v_exp_f32_e32 v198, v131
	s_waitcnt lgkmcnt(3)
	v_mfma_f32_16x16x32_bf16 v[128:131], v[246:249], v[0:3], v[168:171]
	v_add_f32_e32 v199, v159, v188
	v_add_f32_e32 v212, v151, v189
	v_mfma_f32_16x16x32_bf16 v[168:171], v[246:249], v[36:39], v[136:139]
	ds_read_b128 v[188:191], v243 offset:12288
	s_waitcnt lgkmcnt(3)
	v_mfma_f32_16x16x32_bf16 v[164:167], v[192:195], v[12:15], v[164:167]
	v_add_f32_e32 v137, v235, v199
	v_add_f32_e32 v138, v237, v212
	v_mfma_f32_16x16x32_bf16 v[160:163], v[192:195], v[28:31], v[160:163]
	v_cvt_pk_bf16_f32 v136, v152, v153
	v_add_u32_e32 v199, s49, v230
	ds_read_b128 v[192:195], v199
	v_add_f32_e32 v139, v236, v137
	v_add_f32_e32 v138, v238, v138
	s_waitcnt lgkmcnt(3)
	v_mfma_f32_16x16x32_bf16 v[132:135], v[180:183], v[12:15], v[132:135]
	v_cvt_pk_bf16_f32 v137, v154, v155
	v_mfma_f32_16x16x32_bf16 v[152:155], v[180:183], v[28:31], v[172:175]
	s_nop 2
	ds_read_b128 v[172:175], v199 offset:4096
	s_waitcnt lgkmcnt(3)
	v_mfma_f32_16x16x32_bf16 v[176:179], v[184:187], v[12:15], v[176:179]
	v_add_f32_e32 v139, v241, v139
	v_add_f32_e32 v212, v239, v138
	v_mfma_f32_16x16x32_bf16 v[140:143], v[184:187], v[28:31], v[140:143]
	v_cvt_pk_bf16_f32 v138, v156, v157
	ds_read_b128 v[180:183], v199 offset:8192
	v_add_f32_e32 v213, v242, v139
	v_add_f32_e32 v212, v240, v212
	s_waitcnt lgkmcnt(3)
	v_mfma_f32_16x16x32_bf16 v[128:131], v[188:191], v[12:15], v[128:131]
	v_cvt_pk_bf16_f32 v139, v158, v159
	v_mfma_f32_16x16x32_bf16 v[156:159], v[188:191], v[28:31], v[168:171]
	s_nop 2
	ds_read_b128 v[168:171], v199 offset:12288
	s_waitcnt lgkmcnt(3)
	v_mfma_f32_16x16x32_bf16 v[164:167], v[192:195], v[8:11], v[164:167]
	v_mfma_f32_16x16x32_bf16 v[184:187], v[192:195], v[24:27], v[160:163]
	s_nop 2
	v_add_f32_e32 v161, v210, v213
	v_add_f32_e32 v162, v215, v212
	v_cvt_pk_bf16_f32 v160, v144, v145
	v_add_u32_e32 v192, s49, v226
	ds_read_b128 v[188:191], v192 offset:16384
	v_add_f32_e32 v163, v211, v161
	v_add_f32_e32 v162, v214, v162
	s_waitcnt lgkmcnt(3)
	v_mfma_f32_16x16x32_bf16 v[132:135], v[172:175], v[8:11], v[132:135]
	v_cvt_pk_bf16_f32 v161, v146, v147
	v_mfma_f32_16x16x32_bf16 v[144:147], v[172:175], v[24:27], v[152:155]
	s_nop 2
	ds_read_b128 v[152:155], v192 offset:18432
	s_waitcnt lgkmcnt(3)
	v_mfma_f32_16x16x32_bf16 v[172:175], v[180:183], v[8:11], v[176:179]
	v_add_f32_e32 v163, v250, v163
	v_add_f32_e32 v193, v218, v162
	v_mfma_f32_16x16x32_bf16 v[140:143], v[180:183], v[24:27], v[140:143]
	v_cvt_pk_bf16_f32 v162, v148, v149
	ds_read_b128 v[176:179], v192 offset:20480
	v_add_f32_e32 v194, v251, v163
	v_add_f32_e32 v195, v198, v193
	s_waitcnt lgkmcnt(3)
	v_mfma_f32_16x16x32_bf16 v[128:131], v[168:171], v[8:11], v[128:131]
	v_cvt_pk_bf16_f32 v163, v150, v151
	v_mfma_f32_16x16x32_bf16 v[148:151], v[168:171], v[24:27], v[156:159]
	s_nop 2
	ds_read_b128 v[156:159], v192 offset:22528
	s_waitcnt lgkmcnt(3)
	v_mfma_f32_16x16x32_bf16 v[168:171], v[188:191], v[16:19], v[164:167]
	v_cvt_pk_bf16_f32 v164, v235, v236
	v_mfma_f32_16x16x32_bf16 v[180:183], v[188:191], v[32:35], v[184:187]
	v_add_u32_e32 v192, s49, v224
	s_nop 1
	ds_read_b128 v[184:187], v192 offset:16384
	s_waitcnt lgkmcnt(3)
	v_mfma_f32_16x16x32_bf16 v[132:135], v[152:155], v[16:19], v[132:135]
	v_cvt_pk_bf16_f32 v165, v241, v242
	v_mfma_f32_16x16x32_bf16 v[188:191], v[152:155], v[32:35], v[144:147]
	ds_read_b128 v[242:245], v192 offset:18432
	s_waitcnt lgkmcnt(3)
	v_mfma_f32_16x16x32_bf16 v[140:143], v[176:179], v[32:35], v[140:143]
	v_cvt_pk_bf16_f32 v166, v210, v211
	v_mfma_f32_16x16x32_bf16 v[246:249], v[176:179], v[16:19], v[172:175]
	ds_read_b128 v[176:179], v192 offset:20480
	s_waitcnt lgkmcnt(3)
	v_mfma_f32_16x16x32_bf16 v[128:131], v[156:159], v[16:19], v[128:131]
	v_cvt_pk_bf16_f32 v167, v250, v251
	v_mfma_f32_16x16x32_bf16 v[250:253], v[156:159], v[32:35], v[148:151]
	ds_read_b128 v[210:213], v192 offset:22528
	s_waitcnt lgkmcnt(3)
	v_mfma_f32_16x16x32_bf16 v[156:159], v[184:187], v[20:23], v[168:171]
	v_cvt_pk_bf16_f32 v168, v237, v238
	v_mfma_f32_16x16x32_bf16 v[144:147], v[184:187], v[44:47], v[180:183]
	s_waitcnt lgkmcnt(2)
	v_mfma_f32_16x16x32_bf16 v[152:155], v[242:245], v[20:23], v[132:135]
	v_cvt_pk_bf16_f32 v169, v239, v240
	v_mfma_f32_16x16x32_bf16 v[172:175], v[242:245], v[44:47], v[188:191]
	s_waitcnt lgkmcnt(1)
	v_mfma_f32_16x16x32_bf16 v[148:151], v[176:179], v[20:23], v[246:249]
	v_cvt_pk_bf16_f32 v170, v215, v214
	v_mfma_f32_16x16x32_bf16 v[140:143], v[176:179], v[44:47], v[140:143]
	s_waitcnt lgkmcnt(0)
	v_mfma_f32_16x16x32_bf16 v[132:135], v[210:213], v[20:23], v[128:131]
	v_cvt_pk_bf16_f32 v171, v218, v198
	v_mfma_f32_16x16x32_bf16 v[128:131], v[210:213], v[44:47], v[250:253]
	s_lshl_b32 s25, s5, 14
	s_add_i32 s25, s25, 0
	s_add_i32 s25, s25, 0x12000
	v_add_u32_e32 v235, s25, v222
	v_add_u32_e32 v236, s25, v223
	ds_read_b64_tr_b16 v[184:185], v236
	ds_read_b64_tr_b16 v[186:187], v236 offset:4096
	ds_read_b64_tr_b16 v[210:211], v236 offset:8192
	ds_read_b64_tr_b16 v[212:213], v236 offset:12288
	ds_read_b64_tr_b16 v[176:177], v235
	ds_read_b64_tr_b16 v[178:179], v235 offset:4096
	ds_read_b64_tr_b16 v[180:181], v235 offset:8192
	ds_read_b64_tr_b16 v[182:183], v235 offset:12288
	ds_read_b64_tr_b16 v[190:191], v236 offset:4608
	ds_read_b64_tr_b16 v[188:189], v236 offset:512
	ds_read_b64_tr_b16 v[240:241], v236 offset:12800
	ds_read_b64_tr_b16 v[238:239], v236 offset:8704
	s_waitcnt lgkmcnt(10)
	v_mfma_f32_16x16x32_bf16 v[112:115], v[184:187], v[136:139], v[112:115]
	v_mfma_f32_16x16x32_bf16 v[116:119], v[184:187], v[160:163], v[116:119]
	v_max_f32_e32 v184, v156, v157
	s_waitcnt lgkmcnt(8)
	v_mfma_f32_16x16x32_bf16 v[112:115], v[210:213], v[164:167], v[112:115]
	v_max3_f32 v184, v184, v158, v159
	v_max3_f32 v184, v184, v152, v153
	v_max3_f32 v184, v184, v154, v155
	v_mfma_f32_16x16x32_bf16 v[116:119], v[210:213], v[168:171], v[116:119]
	ds_read_b64_tr_b16 v[210:211], v235 offset:512
	ds_read_b64_tr_b16 v[212:213], v235 offset:4608
	ds_read_b64_tr_b16 v[242:243], v235 offset:8704
	ds_read_b64_tr_b16 v[244:245], v235 offset:12800
	s_waitcnt lgkmcnt(10)
	v_mfma_f32_16x16x32_bf16 v[104:107], v[176:179], v[136:139], v[104:107]
	v_mfma_f32_16x16x32_bf16 v[176:179], v[176:179], v[160:163], v[108:111]
	s_waitcnt lgkmcnt(8)
	v_mfma_f32_16x16x32_bf16 v[108:111], v[180:183], v[164:167], v[104:107]
	s_nop 5
	v_max3_f32 v104, v184, v148, v149
	v_max3_f32 v104, v104, v150, v151
	v_max3_f32 v104, v104, v132, v133
	v_max3_f32 v193, v104, v134, v135
	v_mfma_f32_16x16x32_bf16 v[104:107], v[180:183], v[168:171], v[176:179]
	ds_read_b64_tr_b16 v[184:185], v236 offset:1024
	ds_read_b64_tr_b16 v[186:187], v236 offset:5120
	s_nop 0
	ds_read_b64_tr_b16 v[176:177], v236 offset:9216
	ds_read_b64_tr_b16 v[178:179], v236 offset:13312
	s_waitcnt lgkmcnt(10)
	v_mfma_f32_16x16x32_bf16 v[96:99], v[188:191], v[136:139], v[96:99]
	v_max_f32_e32 v180, v144, v145
	s_waitcnt lgkmcnt(8)
	v_mfma_f32_16x16x32_bf16 v[96:99], v[238:241], v[164:167], v[96:99]
	v_max3_f32 v180, v180, v146, v147
	v_max3_f32 v180, v180, v172, v173
	v_max3_f32 v192, v180, v174, v175
	v_mfma_f32_16x16x32_bf16 v[100:103], v[188:191], v[160:163], v[100:103]
	v_mfma_f32_16x16x32_bf16 v[100:103], v[238:241], v[168:171], v[100:103]
	ds_read_b64_tr_b16 v[188:189], v235 offset:1024
	ds_read_b64_tr_b16 v[190:191], v235 offset:5120
	ds_read_b64_tr_b16 v[180:181], v235 offset:9216
	ds_read_b64_tr_b16 v[182:183], v235 offset:13312
	s_waitcnt lgkmcnt(10)
	v_mfma_f32_16x16x32_bf16 v[88:91], v[210:213], v[136:139], v[88:91]
	v_mfma_f32_16x16x32_bf16 v[210:213], v[210:213], v[160:163], v[92:95]
	s_waitcnt lgkmcnt(8)
	v_mfma_f32_16x16x32_bf16 v[92:95], v[242:245], v[164:167], v[88:91]
	s_nop 5
	v_max3_f32 v88, v192, v140, v141
	v_max3_f32 v88, v88, v142, v143
	v_max3_f32 v88, v88, v128, v129
	v_max3_f32 v237, v88, v130, v131
	v_max_f32_e32 v192, v193, v237
	v_cmp_ge_f32_e32 vcc, s62, v192
	v_mfma_f32_16x16x32_bf16 v[88:91], v[242:245], v[168:171], v[210:213]
	s_cmp_eq_u64 vcc, exec
	s_cselect_b64 s[36:37], 0, -1
	v_mov_b32_e32 v192, 1.0
	s_cbranch_scc1 .LBB0_973
	ds_bpermute_b32 v48, v220, v193
	v_max_f32_e32 v49, v193, v193
	v_max_f32_e32 v50, v237, v237
	s_waitcnt lgkmcnt(0)
	v_max_f32_e32 v48, v48, v48
	v_max_f32_e32 v48, v49, v48
	ds_bpermute_b32 v49, v221, v48
	s_waitcnt lgkmcnt(0)
	v_max3_f32 v48, v48, v49, 0
	ds_bpermute_b32 v49, v220, v237
	v_exp_f32_e64 v192, -v48
	v_sub_f32_e32 v156, v156, v48
	v_sub_f32_e32 v157, v157, v48
	v_sub_f32_e32 v158, v158, v48
	s_waitcnt lgkmcnt(0)
	v_max_f32_e32 v49, v49, v49
	v_max_f32_e32 v49, v50, v49
	ds_bpermute_b32 v50, v221, v49
	v_sub_f32_e32 v159, v159, v48
	v_sub_f32_e32 v152, v152, v48
	v_sub_f32_e32 v153, v153, v48
	v_sub_f32_e32 v154, v154, v48
	s_waitcnt lgkmcnt(0)
	v_max3_f32 v49, v49, v50, 0
	v_exp_f32_e64 v193, -v49
	v_pk_add_f32 v[202:203], v[202:203], v[48:49]
	v_sub_f32_e32 v155, v155, v48
	v_pk_add_f32 v[120:121], v[202:203], 0 neg_lo:[1,1] neg_hi:[1,1]
	v_xor_b32_e32 v124, 0x80000000, v203
	v_sub_f32_e32 v151, v151, v48
	v_sub_f32_e32 v150, v150, v48
	v_sub_f32_e32 v149, v149, v48
	v_sub_f32_e32 v148, v148, v48
	v_sub_f32_e32 v135, v135, v48
	v_sub_f32_e32 v134, v134, v48
	v_sub_f32_e32 v133, v133, v48
	v_sub_f32_e32 v132, v132, v48
	v_mov_b32_e32 v121, v120
	v_mov_b32_e32 v122, v120
	v_mov_b32_e32 v123, v120
	v_sub_f32_e32 v144, v144, v49
	v_sub_f32_e32 v145, v145, v49
	v_sub_f32_e32 v146, v146, v49
	v_sub_f32_e32 v147, v147, v49
	v_sub_f32_e32 v172, v172, v49
	v_sub_f32_e32 v173, v173, v49
	v_sub_f32_e32 v174, v174, v49
	v_sub_f32_e32 v175, v175, v49
	v_sub_f32_e32 v143, v143, v49
	v_sub_f32_e32 v142, v142, v49
	v_sub_f32_e32 v141, v141, v49
	v_sub_f32_e32 v140, v140, v49
	v_sub_f32_e32 v131, v131, v49
	v_sub_f32_e32 v130, v130, v49
	v_sub_f32_e32 v129, v129, v49
	v_sub_f32_e32 v128, v128, v49
	v_mov_b32_e32 v125, v124
	v_mov_b32_e32 v126, v124
	v_mov_b32_e32 v127, v124
	v_mov_b32_e32 v48, v120
	v_mov_b32_e32 v49, v120
	v_mov_b32_e32 v50, v120
	v_mov_b32_e32 v51, v120
	v_mov_b32_e32 v52, v124
	v_mov_b32_e32 v53, v124
	v_mov_b32_e32 v54, v124
	v_mov_b32_e32 v55, v124
	s_branch .LBB0_974
